# attention window loop: packed fp32 ops (v_pk_fma/v_pk_mul) split into single ops beside the MFMAs
# speedup vs baseline: 1.0242x; 1.0097x over previous
.LBB0_231:
	s_nop 4
	v_max3_f32 v106, v118, v119, v120
	v_max3_f32 v108, v116, v117, v114
	v_max3_f32 v108, v108, v115, v121
	v_max_f32_e32 v106, v106, v108
	ds_bpermute_b32 v8, v8, v106
	s_waitcnt lgkmcnt(0)
	v_max_f32_e32 v8, v106, v8
	ds_bpermute_b32 v106, v171, v8
	s_waitcnt lgkmcnt(0)
	v_max_f32_e32 v8, v8, v106
	v_cmp_gt_f32_e32 vcc, v8, v153
	s_cbranch_vccz .LBB0_250
	v_max_f32_e32 v8, v8, v8
	v_max_f32_e32 v106, v153, v153
	v_max_f32_e32 v8, v106, v8
	v_sub_f32_e32 v106, v153, v8
	v_exp_f32_e32 v106, v106
	v_mov_b32_e32 v153, v8
	v_mul_f32_e32 v155, v155, v106
	v_mul_f32_e32 v2, v2, v106
	v_mul_f32_e32 v3, v3, v106
	v_mul_f32_e32 v0, v0, v106
	v_mul_f32_e32 v1, v1, v106
	v_mul_f32_e32 v6, v6, v106
	v_mul_f32_e32 v7, v7, v106
	v_mul_f32_e32 v4, v4, v106
	v_mul_f32_e32 v5, v5, v106
	v_mul_f32_e32 v124, v124, v106
	v_mul_f32_e32 v125, v125, v106
	v_mul_f32_e32 v122, v122, v106
	v_mul_f32_e32 v123, v123, v106
	v_mul_f32_e32 v128, v128, v106
	v_mul_f32_e32 v129, v129, v106
	v_mul_f32_e32 v126, v126, v106
	v_mul_f32_e32 v127, v127, v106

.LBB0_241:
	v_mov_b32_e32 v4, v167
	ds_read_b128 v[0:3], v4
	ds_read_b128 v[4:7], v4 offset:64
	s_cmp_gt_u32 s2, 3
	s_cselect_b64 s[36:37], -1, 0
	s_add_i32 s26, s34, s35
	s_waitcnt vmcnt(15) lgkmcnt(1)
	v_mfma_f32_16x16x32_bf16 v[90:93], v[82:85], v[0:3], 0
	s_cmp_lt_u32 s2, 4
	s_cselect_b64 s[38:39], -1, 0
	s_and_b64 s[28:29], s[38:39], exec
	s_waitcnt vmcnt(13)
	v_mfma_f32_16x16x32_bf16 v[0:3], v[86:89], v[0:3], 0
	s_cselect_b32 s2, 0x1e0, s26
	s_lshl_b32 s2, s2, 2
	s_add_i32 s26, s3, s2
	s_waitcnt lgkmcnt(0)
	v_mfma_f32_16x16x32_bf16 v[90:93], v[74:77], v[4:7], v[90:93]
	s_mov_b64 s[28:29], -1
	s_and_b64 vcc, exec, s[36:37]
	s_waitcnt vmcnt(12)
	v_mfma_f32_16x16x32_bf16 v[94:97], v[78:81], v[4:7], v[0:3]
	s_cbranch_vccz .LBB0_243
	s_nop 1
	v_lshl_add_u32 v0, v169, 2, s26
	v_add_u32_e32 v2, 0x43c, v0
	v_add_u32_e32 v4, 0x444, v0
	v_add_u32_e32 v6, 0x44c, v0
	v_add_u32_e32 v0, 0x454, v0
	ds_read2_b32 v[0:1], v0 offset1:1
	ds_read2_b32 v[2:3], v2 offset1:1
	ds_read2_b32 v[4:5], v4 offset1:1
	ds_read2_b32 v[6:7], v6 offset1:1
	s_mov_b32 s2, 0x3e38aa3b
	s_waitcnt lgkmcnt(3)
	v_fma_f32 v98, v96, s2, v0
	v_fma_f32 v99, v97, s2, v1
	s_waitcnt lgkmcnt(2)
	v_fma_f32 v0, v90, s2, v2
	v_fma_f32 v1, v91, s2, v3
	s_waitcnt lgkmcnt(1)
	v_fma_f32 v2, v92, s2, v4
	v_fma_f32 v3, v93, s2, v5
	s_waitcnt lgkmcnt(0)
	v_fma_f32 v4, v94, s2, v6
	v_fma_f32 v5, v95, s2, v7
	v_cndmask_b32_e64 v3, v194, v3, s[82:83]
	v_cndmask_b32_e64 v5, v194, v5, s[78:79]
	v_cndmask_b32_e64 v4, v194, v4, s[80:81]
	v_cndmask_b32_e64 v2, v194, v2, s[84:85]
	v_cndmask_b32_e64 v1, v194, v1, s[86:87]
	v_cndmask_b32_e64 v0, v194, v0, s[72:73]
	v_cndmask_b32_e64 v6, v194, v98, s[76:77]
	v_cndmask_b32_e64 v7, v194, v99, s[74:75]
	s_mov_b64 s[28:29], 0
.LBB0_243:
	s_andn2_b64 vcc, exec, s[28:29]
	s_cbranch_vccnz .LBB0_245
	s_mov_b32 s2, 0x3e38aa3b
	s_nop 3
	v_mul_f32_e32 v6, s2, v96
	v_mul_f32_e32 v7, s2, v97
	v_mul_f32_e32 v2, s2, v92
	v_mul_f32_e32 v3, s2, v93
	v_mul_f32_e32 v4, s2, v94
	v_mul_f32_e32 v5, s2, v95
	v_mul_f32_e32 v0, s2, v90
	v_mul_f32_e32 v1, s2, v91
.LBB0_245:
	s_nop 0
	v_max3_f32 v8, v0, v1, v2
	v_max3_f32 v91, v4, v5, v6
	v_max3_f32 v91, v91, v7, v3
	v_max_f32_e32 v90, v8, v91
	v_mov_b32_e32 v8, v184
	ds_bpermute_b32 v92, v8, v90
	s_waitcnt lgkmcnt(0)
	v_max_f32_e32 v90, v90, v92
	v_mov_b32_e32 v171, v185
	ds_bpermute_b32 v91, v171, v90
	s_waitcnt lgkmcnt(0)
	v_max_f32_e32 v90, v90, v91
	v_cmp_gt_f32_e32 vcc, v90, v152
	s_cbranch_vccz .LBB0_251
	v_max_f32_e32 v90, v90, v90
	v_max_f32_e32 v91, v152, v152
	v_max_f32_e32 v122, v91, v90
	v_sub_f32_e32 v90, v152, v122
	v_exp_f32_e32 v102, v90
	v_mov_b32_e32 v123, v153
	v_mov_b32_e32 v155, v139
	v_mov_b64_e32 v[152:153], v[122:123]
	v_mul_f32_e32 v154, v138, v102
	v_mul_f32_e32 v92, v40, v102
	v_mul_f32_e32 v93, v41, v102
	v_mul_f32_e32 v90, v38, v102
	v_mul_f32_e32 v91, v39, v102
	v_mul_f32_e32 v96, v36, v102
	v_mul_f32_e32 v97, v37, v102
	v_mul_f32_e32 v94, v34, v102
	v_mul_f32_e32 v95, v35, v102
	v_mul_f32_e32 v100, v32, v102
	v_mul_f32_e32 v101, v33, v102
	v_mul_f32_e32 v98, v30, v102
	v_mul_f32_e32 v99, v31, v102
	v_mul_f32_e32 v104, v28, v102
	v_mul_f32_e32 v105, v29, v102
	v_mul_f32_e32 v103, v27, v102
	v_mul_f32_e32 v102, v26, v102
	s_branch .LBB0_252

.LBB0_252:
	v_sub_f32_e32 v0, v0, v122
	v_exp_f32_e32 v0, v0
	v_sub_f32_e32 v1, v1, v122
	v_exp_f32_e32 v1, v1
	v_sub_f32_e32 v2, v2, v122
	v_exp_f32_e32 v2, v2
	v_sub_f32_e32 v3, v3, v122
	v_exp_f32_e32 v3, v3
	v_sub_f32_e32 v4, v4, v122
	v_sub_f32_e32 v5, v5, v122
	v_sub_f32_e32 v6, v6, v122
	v_sub_f32_e32 v7, v7, v122
	v_add_f32_e32 v123, 0, v0
	v_exp_f32_e32 v4, v4
	v_exp_f32_e32 v5, v5
	v_exp_f32_e32 v6, v6
	v_exp_f32_e32 v7, v7
	v_add_f32_e32 v123, v1, v123
	v_add_f32_e32 v123, v2, v123
	v_add_f32_e32 v123, v3, v123
	v_add_f32_e32 v123, v4, v123
	v_cvt_pk_bf16_f32 v0, v0, v1
	v_cvt_pk_bf16_f32 v1, v2, v3
	v_cvt_pk_bf16_f32 v2, v4, v5
	v_cvt_pk_bf16_f32 v3, v6, v7
	v_add_f32_e32 v123, v5, v123
	v_add_f32_e32 v123, v6, v123
	s_waitcnt vmcnt(11)
	v_mfma_f32_16x16x32_bf16 v[90:93], v[54:57], v[0:3], v[90:93]
	v_add_f32_e32 v122, v7, v123
	s_or_b64 s[28:29], s[18:19], s[38:39]
	v_add_f32_e32 v154, v154, v122
	s_waitcnt vmcnt(10)
	v_mfma_f32_16x16x32_bf16 v[94:97], v[50:53], v[0:3], v[94:97]
	s_andn2_b64 vcc, exec, s[28:29]
	s_waitcnt vmcnt(9)
	v_mfma_f32_16x16x32_bf16 v[98:101], v[46:49], v[0:3], v[98:101]
	s_waitcnt vmcnt(8)
	v_mfma_f32_16x16x32_bf16 v[102:105], v[42:45], v[0:3], v[102:105]
	s_cbranch_vccnz .LBB0_259
	v_mov_b32_e32 v4, v168
	ds_read_b128 v[0:3], v4
	ds_read_b128 v[122:125], v4 offset:64
	s_mov_b64 s[28:29], -1
	s_and_b64 vcc, exec, s[36:37]
	s_waitcnt lgkmcnt(1)
	v_mfma_f32_16x16x32_bf16 v[4:7], v[82:85], v[0:3], 0
	v_mfma_f32_16x16x32_bf16 v[82:85], v[86:89], v[0:3], 0
	s_waitcnt lgkmcnt(0)
	v_mfma_f32_16x16x32_bf16 v[74:77], v[74:77], v[122:125], v[4:7]
	v_mfma_f32_16x16x32_bf16 v[78:81], v[78:81], v[122:125], v[82:85]
	s_cbranch_vccz .LBB0_255
	v_lshl_add_u32 v0, v170, 2, s26
	v_add_u32_e32 v2, 0x43c, v0
	s_nop 0
	v_add_u32_e32 v4, 0x444, v0
	v_add_u32_e32 v6, 0x44c, v0
	v_add_u32_e32 v0, 0x454, v0
	ds_read2_b32 v[0:1], v0 offset1:1
	ds_read2_b32 v[2:3], v2 offset1:1
	ds_read2_b32 v[4:5], v4 offset1:1
	ds_read2_b32 v[6:7], v6 offset1:1
	s_mov_b32 s2, 0x3e38aa3b
	s_waitcnt lgkmcnt(3)
	v_fma_f32 v82, v80, s2, v0
	v_fma_f32 v83, v81, s2, v1
	s_waitcnt lgkmcnt(2)
	v_fma_f32 v0, v74, s2, v2
	v_fma_f32 v1, v75, s2, v3
	s_waitcnt lgkmcnt(1)
	v_fma_f32 v2, v76, s2, v4
	v_fma_f32 v3, v77, s2, v5
	s_waitcnt lgkmcnt(0)
	v_fma_f32 v4, v78, s2, v6
	v_fma_f32 v5, v79, s2, v7
	v_cndmask_b32_e64 v3, v194, v3, s[0:1]
	v_cndmask_b32_e64 v5, v194, v5, s[94:95]
	v_cndmask_b32_e64 v4, v194, v4, s[96:97]
	v_cndmask_b32_e64 v2, v194, v2, s[4:5]
	v_cndmask_b32_e64 v1, v194, v1, s[6:7]
	v_cndmask_b32_e64 v0, v194, v0, s[88:89]
	v_cndmask_b32_e64 v6, v194, v82, s[92:93]
	v_cndmask_b32_e64 v7, v194, v83, s[90:91]
	s_mov_b64 s[28:29], 0
.LBB0_255:
	s_andn2_b64 vcc, exec, s[28:29]
	s_cbranch_vccnz .LBB0_257
	s_mov_b32 s2, 0x3e38aa3b
	s_nop 3
	v_mul_f32_e32 v6, s2, v80
	v_mul_f32_e32 v7, s2, v81
	v_mul_f32_e32 v2, s2, v76
	v_mul_f32_e32 v3, s2, v77
	v_mul_f32_e32 v4, s2, v78
	v_mul_f32_e32 v5, s2, v79
	v_mul_f32_e32 v0, s2, v74
	v_mul_f32_e32 v1, s2, v75
.LBB0_257:
	s_nop 3
	v_max3_f32 v74, v0, v1, v2
	v_max3_f32 v76, v4, v5, v6
	v_max3_f32 v76, v76, v7, v3
	v_max_f32_e32 v74, v74, v76
	ds_bpermute_b32 v75, v8, v74
	s_waitcnt lgkmcnt(0)
	v_max_f32_e32 v74, v74, v75
	ds_bpermute_b32 v75, v171, v74
	s_waitcnt lgkmcnt(0)
	v_max_f32_e32 v74, v74, v75
	v_cmp_gt_f32_e32 vcc, v74, v153
	s_cbranch_vccz .LBB0_260
	v_max_f32_e32 v74, v74, v74
	v_max_f32_e32 v75, v153, v153
	v_max_f32_e32 v122, v75, v74
	v_sub_f32_e32 v74, v153, v122
	v_exp_f32_e32 v74, v74
	v_mov_b32_e32 v153, v122
	v_mul_f32_e32 v155, v155, v74
	v_mul_f32_e32 v88, v24, v74
	v_mul_f32_e32 v89, v25, v74
	v_mul_f32_e32 v86, v22, v74
	v_mul_f32_e32 v87, v23, v74
	v_mul_f32_e32 v84, v20, v74
	v_mul_f32_e32 v85, v21, v74
	v_mul_f32_e32 v82, v18, v74
	v_mul_f32_e32 v83, v19, v74
	v_mul_f32_e32 v80, v16, v74
	v_mul_f32_e32 v81, v17, v74
	v_mul_f32_e32 v78, v14, v74
	v_mul_f32_e32 v79, v15, v74
	v_mul_f32_e32 v76, v12, v74
	v_mul_f32_e32 v77, v13, v74
	v_mul_f32_e32 v75, v11, v74
	v_mul_f32_e32 v74, v10, v74
	s_branch .LBB0_261

.LBB0_264:
	s_andn2_b64 vcc, exec, s[38:39]
	s_cbranch_vccnz .LBB0_273
	v_mov_b32_e32 v130, v167
	ds_read_b128 v[134:137], v130
	ds_read_b128 v[156:159], v130 offset:64
	s_mov_b64 s[38:39], -1
	s_and_b64 vcc, exec, s[36:37]
	s_waitcnt vmcnt(15) lgkmcnt(1)
	v_mfma_f32_16x16x32_bf16 v[130:133], v[114:117], v[134:137], 0
	s_waitcnt vmcnt(13)
	v_mfma_f32_16x16x32_bf16 v[134:137], v[118:121], v[134:137], 0
	s_waitcnt lgkmcnt(0)
	v_mfma_f32_16x16x32_bf16 v[130:133], v[110:113], v[156:159], v[130:133]
	s_waitcnt vmcnt(12)
	v_mfma_f32_16x16x32_bf16 v[134:137], v[106:109], v[156:159], v[134:137]
	s_cbranch_vccz .LBB0_267
	v_lshl_add_u32 v158, v169, 2, s26
	v_add_u32_e32 v159, 0x4c0, v158
	v_add_u32_e32 v156, 0x400, v158
	v_add_u32_e32 v161, 0x4c8, v158
	v_add_u32_e32 v174, 0x4d0, v158
	ds_read2_b32 v[158:159], v159 offset1:1
	ds_read2_b32 v[156:157], v156 offset0:47 offset1:54
	ds_read2_b32 v[172:173], v161 offset1:1
	ds_read2_b32 v[174:175], v174 offset1:1
	v_mov_b32_e32 v162, v131
	v_mov_b32_e32 v163, v132
	s_mov_b32 s2, 0x3e38aa3b
	s_waitcnt lgkmcnt(3)
	v_fma_f32 v158, v162, s2, v158
	v_fma_f32 v159, v163, s2, v159
	v_readlane_b32 s28, v255, 33
	v_cndmask_b32_e64 v161, v194, v158, s[44:45]
	v_cndmask_b32_e64 v162, v194, v159, s[42:43]
	v_pk_mov_b32 v[158:159], v[132:133], v[134:135] op_sel:[1,0]
	s_waitcnt lgkmcnt(2)
	v_fmamk_f32 v156, v130, 0x3e38aa3b, v156
	s_waitcnt lgkmcnt(1)
	v_fma_f32 v158, v158, s2, v172
	v_fma_f32 v159, v159, s2, v173
	v_mov_b32_e32 v172, v135
	v_mov_b32_e32 v173, v136
	v_readlane_b32 s29, v255, 34
	s_waitcnt lgkmcnt(0)
	v_fma_f32 v172, v172, s2, v174
	v_fma_f32 v173, v173, s2, v175
	v_fmac_f32_e32 v157, 0x3e38aa3b, v137
	v_cndmask_b32_e64 v160, v194, v156, s[28:29]
	v_cndmask_b32_e64 v163, v194, v158, s[48:49]
	v_cndmask_b32_e64 v158, v194, v159, s[46:47]
	v_cndmask_b32_e64 v159, v194, v172, s[52:53]
	v_cndmask_b32_e64 v156, v194, v173, s[50:51]
	v_cndmask_b32_e64 v157, v194, v157, s[54:55]
	s_mov_b64 s[38:39], 0
.LBB0_267:
	s_andn2_b64 vcc, exec, s[38:39]
	s_cbranch_vccnz .LBB0_269
	s_mov_b32 s2, 0x3e38aa3b
	s_nop 3
	v_mul_f32_e32 v156, s2, v136
	v_mul_f32_e32 v157, s2, v137
	v_mul_f32_e32 v162, s2, v132
	v_mul_f32_e32 v163, s2, v133
	v_mul_f32_e32 v158, s2, v134
	v_mul_f32_e32 v159, s2, v135
	v_mul_f32_e32 v160, s2, v130
	v_mul_f32_e32 v161, s2, v131
.LBB0_269:
	s_nop 2
	v_max3_f32 v130, v160, v161, v162
	v_max3_f32 v132, v158, v159, v156
	v_max3_f32 v132, v132, v157, v163
	v_max_f32_e32 v130, v130, v132
	ds_bpermute_b32 v131, v8, v130
	s_waitcnt lgkmcnt(0)
	v_max_f32_e32 v130, v130, v131
	ds_bpermute_b32 v131, v171, v130
	s_waitcnt lgkmcnt(0)
	v_max_f32_e32 v130, v130, v131
	v_cmp_gt_f32_e32 vcc, v130, v152
	s_cbranch_vccz .LBB0_271
	v_max_f32_e32 v130, v130, v130
	v_max_f32_e32 v131, v152, v152
	v_max_f32_e32 v130, v131, v130
	v_sub_f32_e32 v131, v152, v130
	v_exp_f32_e32 v132, v131
	v_mov_b32_e32 v131, v153
	v_mov_b64_e32 v[152:153], v[130:131]
	v_mul_f32_e32 v154, v154, v132
	v_mul_f32_e32 v92, v92, v132
	v_mul_f32_e32 v93, v93, v132
	v_mul_f32_e32 v90, v90, v132
	v_mul_f32_e32 v91, v91, v132
	v_mul_f32_e32 v96, v96, v132
	v_mul_f32_e32 v97, v97, v132
	v_mul_f32_e32 v94, v94, v132
	v_mul_f32_e32 v95, v95, v132
	v_mul_f32_e32 v100, v100, v132
	v_mul_f32_e32 v101, v101, v132
	v_mul_f32_e32 v98, v98, v132
	v_mul_f32_e32 v99, v99, v132
	v_mul_f32_e32 v104, v104, v132
	v_mul_f32_e32 v105, v105, v132
	v_mul_f32_e32 v102, v102, v132
	v_mul_f32_e32 v103, v103, v132
	s_branch .LBB0_272

.LBB0_273:
	v_mov_b32_e32 v134, v168
	ds_read_b128 v[130:133], v134
	ds_read_b128 v[134:137], v134 offset:64
	s_mov_b64 s[38:39], -1
	s_and_b64 vcc, exec, s[36:37]
	s_waitcnt vmcnt(15) lgkmcnt(1)
	v_mfma_f32_16x16x32_bf16 v[114:117], v[114:117], v[130:133], 0
	s_waitcnt vmcnt(13)
	v_mfma_f32_16x16x32_bf16 v[130:133], v[118:121], v[130:133], 0
	s_waitcnt lgkmcnt(0)
	v_mfma_f32_16x16x32_bf16 v[110:113], v[110:113], v[134:137], v[114:117]
	s_waitcnt vmcnt(12)
	v_mfma_f32_16x16x32_bf16 v[106:109], v[106:109], v[134:137], v[130:133]
	s_cbranch_vccz .LBB0_275
	s_nop 0
	v_lshl_add_u32 v116, v170, 2, s26
	v_add_u32_e32 v117, 0x4c0, v116
	v_add_u32_e32 v114, 0x400, v116
	v_add_u32_e32 v119, 0x4c8, v116
	v_add_u32_e32 v132, 0x4d0, v116
	ds_read2_b32 v[116:117], v117 offset1:1
	ds_read2_b32 v[114:115], v114 offset0:47 offset1:54
	ds_read2_b32 v[130:131], v119 offset1:1
	ds_read2_b32 v[132:133], v132 offset1:1
	v_mov_b32_e32 v120, v111
	v_mov_b32_e32 v121, v112
	s_mov_b32 s2, 0x3e38aa3b
	s_waitcnt lgkmcnt(3)
	v_fma_f32 v116, v120, s2, v116
	v_fma_f32 v117, v121, s2, v117
	s_waitcnt lgkmcnt(2)
	v_fmamk_f32 v114, v110, 0x3e38aa3b, v114
	v_cndmask_b32_e64 v119, v194, v116, s[60:61]
	v_cndmask_b32_e64 v120, v194, v117, s[58:59]
	v_pk_mov_b32 v[116:117], v[112:113], v[106:107] op_sel:[1,0]
	v_fmac_f32_e32 v115, 0x3e38aa3b, v109
	s_waitcnt lgkmcnt(1)
	v_fma_f32 v116, v116, s2, v130
	v_fma_f32 v117, v117, s2, v131
	v_mov_b32_e32 v130, v107
	v_mov_b32_e32 v131, v108
	s_waitcnt lgkmcnt(0)
	v_fma_f32 v130, v130, s2, v132
	v_fma_f32 v131, v131, s2, v133
	v_cndmask_b32_e64 v118, v194, v114, s[56:57]
	v_cndmask_b32_e64 v121, v194, v116, s[64:65]
	v_cndmask_b32_e64 v116, v194, v117, s[62:63]
	v_cndmask_b32_e64 v117, v194, v130, s[68:69]
	v_cndmask_b32_e64 v114, v194, v131, s[66:67]
	v_cndmask_b32_e64 v115, v194, v115, s[70:71]
	s_mov_b64 s[38:39], 0
.LBB0_275:
	s_andn2_b64 vcc, exec, s[38:39]
	s_cbranch_vccnz .LBB0_231
	s_mov_b32 s2, 0x3e38aa3b
	s_nop 3
	v_mul_f32_e32 v114, s2, v108
	v_mul_f32_e32 v115, s2, v109
	v_mul_f32_e32 v120, s2, v112
	v_mul_f32_e32 v121, s2, v113
	v_mul_f32_e32 v116, s2, v106
	v_mul_f32_e32 v117, s2, v107
	v_mul_f32_e32 v118, s2, v110
	v_mul_f32_e32 v119, s2, v111
	s_branch .LBB0_231
